# norm work queues split per XCD-aligned row range (bid%8) to match GEMM tile ownership for L2 locality
# speedup vs baseline: 1.0087x; 1.0009x over previous
; DI int tidx() { int t = threadIdx.x; asm volatile("" : "+v"(t)); return t; }
; DI void norm_dyn(const Params& p, int layer, int which, int row0, int row1, unsigned* ctr) {
;   const int tid = tidx(), lane = tid & 63, wid = tid >> 6;
;   const int nchunk = (row1 - row0) >> 5;
;   while (true) {
;     int ch = grab(ctr);
;     if (ch >= nchunk) break;
;     norm_rows<4>(p, layer, which, row0 + ch * 32 + wid, 8, lane);
.LBB0_195:
	v_readlane_b32 s0, v252, 35
	v_readlane_b32 s1, v252, 36
	s_mov_b32 s15, s1
	v_readlane_b32 s0, v254, 40
	v_readlane_b32 s1, v254, 41
	s_mov_b32 s1, s15
	s_mov_b32 s2, s0
	v_writelane_b32 v254, s2, 40
	s_lshl_b64 s[0:1], s[0:1], 2
	v_mov_b32_e32 v0, v213
	v_writelane_b32 v254, s3, 41
	s_add_u32 s2, s58, s0
	s_addc_u32 s3, s59, s1
	v_readlane_b32 s0, v254, 33
	v_readlane_b32 s1, v254, 34
	s_mov_b32 s1, s15
	s_mul_hi_u32 s13, s0, 5
	s_mul_i32 s12, s0, 5
	s_lshl_b32 s14, s0, 10
	v_writelane_b32 v252, s0, 35
	s_nop 0
	v_ashrrev_i32_e32 v106, 6, v0
	v_writelane_b32 v252, s1, 36
	v_lshlrev_b32_e32 v0, 2, v0
	v_readlane_b32 s36, v252, 19
	s_lshl_b64 s[0:1], s[14:15], 2
	v_readlane_b32 s50, v252, 33
	v_and_b32_e32 v2, 0xfc, v0
	v_readlane_b32 s51, v252, 34
	s_add_u32 s0, s50, s0
	s_addc_u32 s1, s51, s1
	v_lshlrev_b32_e32 v0, 2, v2
	v_or_b32_e32 v4, 0x100, v2
	v_or_b32_e32 v6, 0x200, v2
	v_or_b32_e32 v8, 0x300, v2
	s_waitcnt vmcnt(0)
	v_lshl_add_u64 v[74:75], s[0:1], 0, v[0:1]
	v_lshlrev_b32_e32 v0, 1, v2
	v_lshl_add_u64 v[76:77], s[86:87], 0, v[0:1]
	v_lshlrev_b32_e32 v0, 2, v2
	v_lshlrev_b32_e32 v78, 2, v4
	v_lshlrev_b32_e32 v80, 2, v6
	v_lshlrev_b32_e32 v82, 2, v8
	v_readlane_b32 s37, v252, 20
	v_readlane_b32 s38, v252, 21
	v_readlane_b32 s39, v252, 22
	v_readlane_b32 s40, v252, 23
	v_readlane_b32 s41, v252, 24
	v_readlane_b32 s42, v252, 25
	v_readlane_b32 s43, v252, 26
	v_readlane_b32 s44, v252, 27
	v_readlane_b32 s45, v252, 28
	v_readlane_b32 s46, v252, 29
	v_readlane_b32 s47, v252, 30
	v_readlane_b32 s48, v252, 31
	v_readlane_b32 s49, v252, 32
	v_readlane_b32 s14, v253, 43
	s_nop 3
	s_and_b32 s14, s14, 7
	s_lshl_b32 s15, s14, 8
	s_add_u32 s2, s2, s15
	s_addc_u32 s3, s3, 0
	s_add_u32 s2, s2, 0x100
	s_addc_u32 s3, s3, 0
	s_lshl_b32 s14, s14, 11
	v_add_u32_e32 v106, s14, v106
	s_branch .LBB0_197

; template <int R>
; DI void norm_rows(const Params& p, int layer, int which, int t0, int tstep, int lane) {
;   const float* g = (which ? p.norm_ffn : p.norm_attn) + layer * DM;
;   const float* md = p.mod + ((size_t)layer * 5 + mb_of(t0)) * 6144 + (which ? 3 * 1024 : 0);
;   float4 v[R][4];
;   float ss[R];
; #pragma unroll
;   for (int r = 0; r < R; ++r) {
;     const float* xr = which ? (const float*)xrow_dst(p, t0 + r * tstep) : xrow_src(p, layer, t0 + r * tstep);
; #pragma unroll
;     for (int j = 0; j < 4; ++j) v[r][j] = *(const float4*)(xr + lane * 4 + 256 * j);
; DI void norm_dyn(const Params& p, int layer, int which, int row0, int row1, unsigned* ctr) {
;     ...
;   while (true) {
;     int ch = grab(ctr);
;     if (ch >= nchunk) break;
;     norm_rows<4>(p, layer, which, row0 + ch * 32 + wid, 8, lane);
.LBB0_201:
	s_or_b64 exec, exec, s[0:1]
	s_waitcnt vmcnt(0) lgkmcnt(0)
	s_barrier
	ds_read_b32 v2, v1
	s_movk_i32 s0, 0x3f
	s_waitcnt lgkmcnt(0)
	s_barrier
	v_cmp_lt_i32_e32 vcc, s0, v2
	s_mov_b64 s[0:1], -1
	s_cbranch_vccnz .LBB0_196
	v_lshl_add_u32 v54, v2, 5, v106
	s_movk_i32 s0, 0x4000
	v_mov_b64_e32 v[2:3], s[64:65]
	v_mov_b64_e32 v[4:5], s[76:77]
	v_add_u32_e32 v6, 0xffffc000, v54
	v_ashrrev_i32_e32 v55, 31, v54
	v_cmp_gt_i32_e32 vcc, s0, v54
	v_add_u32_e32 v56, 8, v54
	s_movk_i32 s0, 0x3ff8
	v_cndmask_b32_e32 v7, 0, v55, vcc
	v_cndmask_b32_e32 v6, v6, v54, vcc
	v_cndmask_b32_e32 v3, v3, v5, vcc
	v_cndmask_b32_e32 v2, v2, v4, vcc
	v_lshlrev_b64 v[4:5], 12, v[6:7]
	v_lshl_add_u64 v[2:3], v[2:3], 0, v[4:5]
	v_lshl_add_u64 v[2:3], v[2:3], 0, v[0:1]
	v_add_u32_e32 v4, 0xffffc008, v54
	v_ashrrev_i32_e32 v57, 31, v56
	v_cmp_gt_i32_e32 vcc, s0, v54
	v_mov_b64_e32 v[12:13], s[64:65]
	v_mov_b64_e32 v[22:23], s[76:77]
	global_load_dwordx4 v[18:21], v[2:3], off
	global_load_dwordx4 v[14:17], v[2:3], off offset:1024
	v_cndmask_b32_e32 v11, 0, v57, vcc
	v_cndmask_b32_e32 v10, v4, v56, vcc
	global_load_dwordx4 v[6:9], v[2:3], off offset:2048
	s_nop 0
	global_load_dwordx4 v[2:5], v[2:3], off offset:3072
	s_movk_i32 s0, 0x3ff0
	v_lshlrev_b64 v[10:11], 12, v[10:11]
	v_add_u32_e32 v60, 16, v54
	v_add_u32_e32 v24, 0xffffc010, v54
	v_cndmask_b32_e32 v13, v13, v23, vcc
	v_cndmask_b32_e32 v12, v12, v22, vcc
	v_cmp_gt_i32_e64 s[0:1], s0, v54
	v_add_u32_e32 v62, 24, v54
	s_movk_i32 s14, 0x3fe8
	v_lshl_add_u64 v[10:11], v[12:13], 0, v[10:11]
	v_cndmask_b32_e64 v12, v24, v60, s[0:1]
	v_add_u32_e32 v24, 0xffffc018, v54
	v_ashrrev_i32_e32 v63, 31, v62
	v_cmp_gt_i32_e32 vcc, s14, v54
	v_ashrrev_i32_e32 v61, 31, v60
	v_lshl_add_u64 v[10:11], v[10:11], 0, v[0:1]
	v_cndmask_b32_e32 v25, 0, v63, vcc
	v_cndmask_b32_e32 v24, v24, v62, vcc
	v_cndmask_b32_e64 v13, 0, v61, s[0:1]
	v_lshlrev_b64 v[64:65], 12, v[24:25]
	v_mov_b64_e32 v[24:25], s[64:65]
	v_mov_b64_e32 v[26:27], s[76:77]
	global_load_dwordx4 v[46:49], v[10:11], off
	global_load_dwordx4 v[30:33], v[10:11], off offset:1024
	v_lshlrev_b64 v[22:23], 12, v[12:13]
	global_load_dwordx4 v[34:37], v[10:11], off offset:2048
	s_nop 0
	global_load_dwordx4 v[10:13], v[10:11], off offset:3072
	v_min_i32_e32 v40, 0x4000, v54
	v_cndmask_b32_e64 v25, v25, v27, s[0:1]
	v_cndmask_b32_e64 v24, v24, v26, s[0:1]
	v_lshl_add_u64 v[22:23], v[24:25], 0, v[22:23]
	v_lshl_add_u64 v[38:39], v[22:23], 0, v[0:1]
	global_load_dwordx4 v[26:29], v[38:39], off
	global_load_dwordx4 v[22:25], v[38:39], off offset:1024
	v_ashrrev_i32_e32 v40, 12, v40
	v_ashrrev_i32_e32 v41, 31, v40
	v_lshl_add_u64 v[40:41], s[12:13], 0, v[40:41]
	v_mov_b64_e32 v[42:43], s[62:63]
	s_movk_i32 s14, 0x6000
	v_mad_u64_u32 v[42:43], s[0:1], v40, s14, v[42:43]
	v_mad_i32_i24 v43, v41, s14, v43
	v_lshl_add_u64 v[66:67], v[42:43], 0, s[22:23]
	v_lshl_add_u64 v[68:69], v[42:43], 0, s[96:97]
	global_load_dwordx4 v[42:45], v[38:39], off offset:2048
	s_nop 0
	global_load_dwordx4 v[38:41], v[38:39], off offset:3072
	v_lshlrev_b64 v[54:55], 11, v[54:55]
	v_mov_b64_e32 v[50:51], s[76:77]
	v_mov_b64_e32 v[52:53], s[64:65]
	v_lshl_add_u64 v[70:71], v[68:69], 0, v[0:1]
	v_lshl_add_u64 v[90:91], v[76:77], 0, v[54:55]
	v_lshlrev_b64 v[54:55], 11, v[56:57]
	v_lshl_add_u64 v[88:89], v[76:77], 0, v[54:55]
	v_lshlrev_b64 v[54:55], 11, v[60:61]
	global_load_dwordx4 v[108:111], v[70:71], off
	v_mov_b32_e32 v79, v1
	v_lshl_add_u64 v[86:87], v[76:77], 0, v[54:55]
	v_lshlrev_b64 v[54:55], 11, v[62:63]
	global_load_dwordx4 v[112:115], v[74:75], off
	v_lshl_add_u64 v[116:117], v[68:69], 0, v[78:79]
	v_mov_b32_e32 v81, v1
	v_mov_b32_e32 v83, v1
	v_lshl_add_u64 v[72:73], v[66:67], 0, v[0:1]
	v_lshl_add_u64 v[58:59], v[66:67], 0, v[78:79]
	v_lshl_add_u64 v[96:97], v[66:67], 0, v[80:81]
	v_lshl_add_u64 v[92:93], v[66:67], 0, v[82:83]
	v_lshl_add_u64 v[84:85], v[76:77], 0, v[54:55]
	global_load_dwordx4 v[116:119], v[116:117], off
	s_nop 0
	global_load_dwordx4 v[120:123], v[74:75], off offset:1024
	v_lshl_add_u64 v[124:125], v[68:69], 0, v[80:81]
	global_load_dwordx4 v[124:127], v[124:125], off
	s_nop 0
	global_load_dwordx4 v[128:131], v[74:75], off offset:2048
	v_cndmask_b32_e32 v51, v53, v51, vcc
	v_cndmask_b32_e32 v50, v52, v50, vcc
	v_lshl_add_u64 v[50:51], v[50:51], 0, v[64:65]
	v_xor_b32_e32 v64, 16, v211
	v_lshl_add_u64 v[68:69], v[68:69], 0, v[82:83]
	global_load_dwordx4 v[132:135], v[68:69], off
	global_load_dwordx4 v[136:139], v[74:75], off offset:3072
	s_waitcnt vmcnt(0) lgkmcnt(0)
; template <int R>
; DI void norm_rows(const Params& p, int layer, int which, int t0, int tstep, int lane) {
;     ...
; #pragma unroll
;   for (int r = 0; r < R; ++r) {
;     ss[r] = 0.f;
; #pragma unroll
;     for (int j = 0; j < 4; ++j) ss[r] += v[r][j].x * v[r][j].x + v[r][j].y * v[r][j].y + v[r][j].z * v[r][j].z + v[r][j].w * v[r][j].w;
;   }
; #pragma unroll
;   for (int o = 32; o >= 1; o >>= 1)
; #pragma unroll
;     for (int r = 0; r < R; ++r) ss[r] += __shfl_xor(ss[r], o);
; #pragma unroll
;   for (int r = 0; r < R; ++r) ss[r] = rsqrtf(ss[r] * (1.f / 1024.f) + EPSV);
;   float4 mm[4], sh[4];
; #pragma unroll
;   for (int j = 0; j < 4; ++j) {
;     int col = lane * 4 + 256 * j;
;     float4 gg = *(const float4*)(g + col);
;     float4 sc = *(const float4*)(md + 1024 + col);
;     sh[j] = *(const float4*)(md + col);
;     mm[j] = make_float4(gg.x * (1.f + sc.x), gg.y * (1.f + sc.y), gg.z * (1.f + sc.z), gg.w * (1.f + sc.w));
;   }
	v_mov_b32_e32 v62, v19
	v_mov_b32_e32 v63, v15
	v_mov_b32_e32 v60, v18
	v_mov_b32_e32 v61, v14
	v_pk_mul_f32 v[62:63], v[62:63], v[62:63]
	v_mov_b32_e32 v54, v20
	v_mov_b32_e32 v55, v16
	v_pk_fma_f32 v[60:61], v[60:61], v[60:61], v[62:63]
	v_mov_b32_e32 v66, v7
	v_mov_b32_e32 v67, v3
	v_mov_b32_e32 v56, v21
	v_mov_b32_e32 v57, v17
	v_pk_fma_f32 v[54:55], v[54:55], v[54:55], v[60:61]
	v_mov_b32_e32 v62, v6
	v_mov_b32_e32 v63, v2
	v_pk_mul_f32 v[66:67], v[66:67], v[66:67]
	v_pk_fma_f32 v[54:55], v[56:57], v[56:57], v[54:55]
	v_mov_b32_e32 v56, v8
	v_mov_b32_e32 v57, v4
	v_pk_fma_f32 v[62:63], v[62:63], v[62:63], v[66:67]
	v_mov_b32_e32 v60, v9
	v_mov_b32_e32 v61, v5
	v_pk_fma_f32 v[56:57], v[56:57], v[56:57], v[62:63]
	v_xor_b32_e32 v105, 1, v211
	v_pk_fma_f32 v[56:57], v[60:61], v[60:61], v[56:57]
	s_mov_b32 s0, 0x358637bd
	v_mov_b32_e32 v53, v56
	v_mov_b32_e32 v94, v47
	v_mov_b32_e32 v95, v31
	v_mov_b32_e32 v66, v46
	v_mov_b32_e32 v67, v30
	v_pk_mul_f32 v[94:95], v[94:95], v[94:95]
	v_mov_b32_e32 v60, v48
	v_mov_b32_e32 v61, v32
	v_pk_fma_f32 v[66:67], v[66:67], v[66:67], v[94:95]
	v_mov_b32_e32 v98, v35
	v_mov_b32_e32 v99, v11
	v_mov_b32_e32 v62, v49
	v_mov_b32_e32 v63, v33
	v_pk_fma_f32 v[60:61], v[60:61], v[60:61], v[66:67]
	v_mov_b32_e32 v94, v34
	v_mov_b32_e32 v95, v10
	v_pk_mul_f32 v[98:99], v[98:99], v[98:99]
	v_pk_fma_f32 v[60:61], v[62:63], v[62:63], v[60:61]
	v_mov_b32_e32 v62, v36
	v_mov_b32_e32 v63, v12
	v_pk_fma_f32 v[94:95], v[94:95], v[94:95], v[98:99]
	v_mov_b32_e32 v100, v27
	v_mov_b32_e32 v101, v23
	v_mov_b32_e32 v66, v37
	v_mov_b32_e32 v67, v13
	v_pk_fma_f32 v[62:63], v[62:63], v[62:63], v[94:95]
	v_mov_b32_e32 v98, v26
	v_mov_b32_e32 v99, v22
	v_pk_mul_f32 v[100:101], v[100:101], v[100:101]
	v_pk_fma_f32 v[62:63], v[66:67], v[66:67], v[62:63]
	v_mov_b32_e32 v66, v28
	v_mov_b32_e32 v67, v24
	v_pk_fma_f32 v[98:99], v[98:99], v[98:99], v[100:101]
	v_mov_b32_e32 v94, v29
	v_mov_b32_e32 v95, v25
	v_pk_fma_f32 v[66:67], v[66:67], v[66:67], v[98:99]
	v_mov_b32_e32 v52, v62
	v_pk_fma_f32 v[94:95], v[94:95], v[94:95], v[66:67]
	v_lshl_add_u64 v[66:67], v[50:51], 0, v[0:1]
	v_and_b32_e32 v50, 64, v211
	v_add_u32_e32 v79, 64, v50
	v_xor_b32_e32 v50, 32, v211
	v_cmp_lt_i32_e32 vcc, v50, v79
	v_mov_b32_e32 v51, v54
	v_mov_b32_e32 v54, v61
	v_cndmask_b32_e32 v50, v211, v50, vcc
	v_lshlrev_b32_e32 v81, 2, v50
	v_mov_b32_e32 v50, v60
	v_pk_add_f32 v[50:51], v[50:51], v[54:55]
	v_mov_b32_e32 v56, v63
	v_pk_add_f32 v[50:51], v[50:51], v[52:53]
	v_cmp_lt_i32_e32 vcc, v64, v79
	v_pk_add_f32 v[50:51], v[50:51], v[56:57]
	ds_bpermute_b32 v53, v81, v51
	ds_bpermute_b32 v52, v81, v50
	v_cndmask_b32_e32 v60, v211, v64, vcc
	v_lshlrev_b32_e32 v83, 2, v60
	v_xor_b32_e32 v64, 8, v211
	v_cmp_lt_i32_e32 vcc, v64, v79
	s_waitcnt lgkmcnt(0)
	v_pk_add_f32 v[60:61], v[50:51], v[52:53]
	ds_bpermute_b32 v63, v83, v61
	ds_bpermute_b32 v62, v83, v60
	v_cndmask_b32_e32 v50, v211, v64, vcc
	v_lshlrev_b32_e32 v107, 2, v50
	global_load_dwordx4 v[54:57], v[72:73], off
	global_load_dwordx4 v[50:53], v[58:59], off
	s_waitcnt lgkmcnt(0)
	v_pk_add_f32 v[68:69], v[60:61], v[62:63]
	ds_bpermute_b32 v71, v107, v69
	ds_bpermute_b32 v70, v107, v68
	v_xor_b32_e32 v58, 4, v211
	v_cmp_lt_i32_e32 vcc, v58, v79
	v_xor_b32_e32 v72, 2, v211
	v_mov_b32_e32 v104, v43
	v_cndmask_b32_e32 v58, v211, v58, vcc
	v_lshlrev_b32_e32 v145, 2, v58
	s_waitcnt lgkmcnt(0)
	v_pk_add_f32 v[68:69], v[68:69], v[70:71]
	ds_bpermute_b32 v71, v145, v69
	ds_bpermute_b32 v70, v145, v68
	global_load_dwordx4 v[62:65], v[66:67], off
	global_load_dwordx4 v[58:61], v[66:67], off offset:1024
	v_cmp_lt_i32_e32 vcc, v72, v79
	v_mov_b32_e32 v102, v42
	v_mov_b32_e32 v103, v38
	v_cndmask_b32_e32 v72, v211, v72, vcc
	v_lshlrev_b32_e32 v146, 2, v72
	s_waitcnt lgkmcnt(0)
	v_pk_add_f32 v[140:141], v[68:69], v[70:71]
	global_load_dwordx4 v[70:73], v[66:67], off offset:2048
	s_nop 0
	global_load_dwordx4 v[66:69], v[66:67], off offset:3072
	ds_bpermute_b32 v143, v146, v141
	ds_bpermute_b32 v142, v146, v140
	v_cmp_lt_i32_e32 vcc, v105, v79
	v_mov_b32_e32 v100, v44
	v_mov_b32_e32 v101, v40
	v_cndmask_b32_e32 v79, v211, v105, vcc
	v_lshlrev_b32_e32 v79, 2, v79
	s_waitcnt lgkmcnt(0)
	v_pk_add_f32 v[140:141], v[140:141], v[142:143]
	ds_bpermute_b32 v143, v79, v141
	ds_bpermute_b32 v142, v79, v140
	v_mov_b32_e32 v105, v39
	v_pk_mul_f32 v[104:105], v[104:105], v[104:105]
	s_mov_b32 s16, 0x3a800000
	v_pk_fma_f32 v[102:103], v[102:103], v[102:103], v[104:105]
	v_mov_b64_e32 v[104:105], s[0:1]
	v_pk_fma_f32 v[100:101], v[100:101], v[100:101], v[102:103]
	s_waitcnt lgkmcnt(0)
	v_pk_add_f32 v[102:103], v[140:141], v[142:143]
	s_mov_b32 s14, 0x800000
	v_pk_fma_f32 v[102:103], v[102:103], s[16:17], v[104:105] op_sel_hi:[1,0,0]
	v_mov_b32_e32 v98, v45
	v_mul_f32_e32 v140, 0x4b800000, v103
	v_cmp_gt_f32_e32 vcc, s14, v103
	v_mov_b32_e32 v99, v41
	v_cmp_gt_f32_e64 s[0:1], s14, v102
	v_cndmask_b32_e32 v103, v103, v140, vcc
	v_mul_f32_e32 v140, 0x4b800000, v102
	v_rsq_f32_e32 v103, v103
	v_cndmask_b32_e64 v102, v102, v140, s[0:1]
	v_pk_fma_f32 v[140:141], v[98:99], v[98:99], v[100:101]
	v_pk_add_f32 v[100:101], v[108:109], 1.0 op_sel_hi:[1,0]
	v_rsq_f32_e32 v102, v102
	v_pk_mul_f32 v[108:109], v[112:113], v[100:101]
	v_pk_add_f32 v[100:101], v[110:111], 1.0 op_sel_hi:[1,0]
	v_mul_f32_e32 v98, 0x45800000, v103
	v_pk_mul_f32 v[110:111], v[114:115], v[100:101]
	v_pk_add_f32 v[100:101], v[116:117], 1.0 op_sel_hi:[1,0]
	v_cndmask_b32_e32 v142, v103, v98, vcc
	v_pk_mul_f32 v[112:113], v[120:121], v[100:101]
	v_pk_add_f32 v[100:101], v[118:119], 1.0 op_sel_hi:[1,0]
	v_mul_f32_e32 v98, 0x45800000, v102
	v_pk_mul_f32 v[114:115], v[122:123], v[100:101]
	v_pk_add_f32 v[100:101], v[124:125], 1.0 op_sel_hi:[1,0]
	v_cndmask_b32_e64 v144, v102, v98, s[0:1]
	v_pk_mul_f32 v[116:117], v[128:129], v[100:101]
	v_pk_add_f32 v[100:101], v[126:127], 1.0 op_sel_hi:[1,0]
	global_load_dwordx4 v[96:99], v[96:97], off
	v_pk_mul_f32 v[118:119], v[130:131], v[100:101]
	global_load_dwordx4 v[100:103], v[92:93], off
	v_pk_mul_f32 v[18:19], v[18:19], v[142:143] op_sel_hi:[1,0]
	v_pk_mul_f32 v[20:21], v[20:21], v[142:143] op_sel_hi:[1,0]
	v_pk_mul_f32 v[14:15], v[14:15], v[142:143] op_sel_hi:[1,0]
	v_pk_mul_f32 v[16:17], v[16:17], v[142:143] op_sel_hi:[1,0]
	v_pk_mul_f32 v[32:33], v[32:33], v[144:145] op_sel_hi:[1,0]
	v_pk_add_f32 v[92:93], v[132:133], 1.0 op_sel_hi:[1,0]
	v_pk_add_f32 v[120:121], v[134:135], 1.0 op_sel_hi:[1,0]
	v_pk_mul_f32 v[92:93], v[136:137], v[92:93]
	v_pk_mul_f32 v[120:121], v[138:139], v[120:121]
	v_pk_mul_f32 v[2:3], v[2:3], v[142:143] op_sel_hi:[1,0]
	s_waitcnt vmcnt(0)
; template <int R>
; DI void norm_rows(const Params& p, int layer, int which, int t0, int tstep, int lane) {
;     ...
; #pragma unroll
;   for (int r = 0; r < R; ++r) {
;     ss[r] = 0.f;
; #pragma unroll
;     for (int j = 0; j < 4; ++j) ss[r] += v[r][j].x * v[r][j].x + v[r][j].y * v[r][j].y + v[r][j].z * v[r][j].z + v[r][j].w * v[r][j].w;
;   }
; #pragma unroll
;   for (int o = 32; o >= 1; o >>= 1)
; #pragma unroll
;     for (int r = 0; r < R; ++r) ss[r] += __shfl_xor(ss[r], o);
; #pragma unroll
;   for (int r = 0; r < R; ++r) ss[r] = rsqrtf(ss[r] * (1.f / 1024.f) + EPSV);
;   float4 mm[4], sh[4];
; #pragma unroll
;   for (int j = 0; j < 4; ++j) {
;     int col = lane * 4 + 256 * j;
;     float4 gg = *(const float4*)(g + col);
;     float4 sc = *(const float4*)(md + 1024 + col);
;     sh[j] = *(const float4*)(md + col);
;     mm[j] = make_float4(gg.x * (1.f + sc.x), gg.y * (1.f + sc.y), gg.z * (1.f + sc.z), gg.w * (1.f + sc.w));
;   }
; #pragma unroll
;   for (int j = 0; j < 4; ++j) {
;     int col = lane * 4 + 256 * j;
; #pragma unroll
;     for (int r = 0; r < R; ++r)
;       *(uint2*)(p.H + (size_t)(t0 + r * tstep) * LDK + col) =
;           make_uint2(pack_bf16(v[r][j].x * ss[r] * mm[j].x + sh[j].x, v[r][j].y * ss[r] * mm[j].y + sh[j].y),
;                      pack_bf16(v[r][j].z * ss[r] * mm[j].z + sh[j].z, v[r][j].w * ss[r] * mm[j].w + sh[j].w));
	v_pk_fma_f32 v[18:19], v[18:19], v[108:109], v[54:55]
	v_pk_fma_f32 v[20:21], v[20:21], v[110:111], v[56:57]
	v_cvt_pk_bf16_f32 v18, v18, v19
	v_cvt_pk_bf16_f32 v19, v20, v21
	v_pk_mul_f32 v[20:21], v[46:47], v[144:145] op_sel_hi:[1,0]
	v_pk_mul_f32 v[46:47], v[48:49], v[144:145] op_sel_hi:[1,0]
	v_pk_fma_f32 v[14:15], v[14:15], v[112:113], v[50:51]
	v_pk_fma_f32 v[16:17], v[16:17], v[114:115], v[52:53]
	v_pk_fma_f32 v[20:21], v[108:109], v[20:21], v[54:55]
	v_pk_fma_f32 v[46:47], v[46:47], v[110:111], v[56:57]
	v_cvt_pk_bf16_f32 v14, v14, v15
	v_cvt_pk_bf16_f32 v15, v16, v17
	v_pk_mul_f32 v[16:17], v[30:31], v[144:145] op_sel_hi:[1,0]
	v_mov_b32_e32 v122, v63
	v_mov_b32_e32 v123, v59
	v_mov_b32_e32 v48, v62
	v_mov_b32_e32 v49, v58
	v_pk_mul_f32 v[122:123], v[122:123], v[122:123]
	v_mov_b32_e32 v30, v64
	v_mov_b32_e32 v31, v60
	v_pk_fma_f32 v[48:49], v[48:49], v[48:49], v[122:123]
	v_mov_b32_e32 v124, v71
	v_mov_b32_e32 v125, v67
	v_cvt_pk_bf16_f32 v20, v20, v21
	v_cvt_pk_bf16_f32 v21, v46, v47
	v_mov_b32_e32 v46, v65
	v_mov_b32_e32 v47, v61
	v_pk_fma_f32 v[30:31], v[30:31], v[30:31], v[48:49]
	v_mov_b32_e32 v122, v70
	v_mov_b32_e32 v123, v66
	v_pk_mul_f32 v[124:125], v[124:125], v[124:125]
	v_pk_fma_f32 v[30:31], v[46:47], v[46:47], v[30:31]
	v_mov_b32_e32 v46, v72
	v_mov_b32_e32 v47, v68
	v_pk_fma_f32 v[122:123], v[122:123], v[122:123], v[124:125]
	v_mov_b32_e32 v48, v73
	v_mov_b32_e32 v49, v69
	v_pk_fma_f32 v[46:47], v[46:47], v[46:47], v[122:123]
	v_pk_fma_f32 v[16:17], v[16:17], v[112:113], v[50:51]
	v_pk_fma_f32 v[46:47], v[48:49], v[48:49], v[46:47]
	v_mov_b32_e32 v48, v30
	v_mov_b32_e32 v49, v94
	v_mov_b32_e32 v94, v31
	v_pk_add_f32 v[30:31], v[48:49], v[94:95]
	v_mov_b32_e32 v48, v46
	v_mov_b32_e32 v49, v140
	v_pk_add_f32 v[30:31], v[30:31], v[48:49]
	v_mov_b32_e32 v140, v47
	v_pk_add_f32 v[30:31], v[30:31], v[140:141]
	ds_bpermute_b32 v47, v81, v31
	ds_bpermute_b32 v46, v81, v30
	v_pk_fma_f32 v[32:33], v[32:33], v[114:115], v[52:53]
	v_cvt_pk_bf16_f32 v16, v16, v17
	v_cvt_pk_bf16_f32 v17, v32, v33
	v_pk_mul_f32 v[4:5], v[4:5], v[142:143] op_sel_hi:[1,0]
	s_waitcnt lgkmcnt(0)
	v_pk_add_f32 v[30:31], v[30:31], v[46:47]
	ds_bpermute_b32 v33, v83, v31
	ds_bpermute_b32 v32, v83, v30
	v_pk_mul_f32 v[12:13], v[12:13], v[144:145] op_sel_hi:[1,0]
	v_pk_mul_f32 v[6:7], v[6:7], v[142:143] op_sel_hi:[1,0]
	v_pk_mul_f32 v[8:9], v[8:9], v[142:143] op_sel_hi:[1,0]
	s_mov_b64 s[0:1], 0
	s_waitcnt lgkmcnt(0)
	v_pk_add_f32 v[30:31], v[30:31], v[32:33]
	ds_bpermute_b32 v33, v107, v31
	ds_bpermute_b32 v32, v107, v30
	v_pk_fma_f32 v[6:7], v[6:7], v[116:117], v[96:97]
	v_pk_fma_f32 v[8:9], v[8:9], v[118:119], v[98:99]
	s_waitcnt lgkmcnt(0)
	v_pk_add_f32 v[30:31], v[30:31], v[32:33]
	ds_bpermute_b32 v33, v145, v31
	ds_bpermute_b32 v32, v145, v30
	v_pk_fma_f32 v[2:3], v[2:3], v[92:93], v[100:101]
	v_pk_fma_f32 v[4:5], v[4:5], v[120:121], v[102:103]
	v_cvt_pk_bf16_f32 v2, v2, v3
	v_cvt_pk_bf16_f32 v3, v4, v5
	s_waitcnt lgkmcnt(0)
	v_pk_add_f32 v[30:31], v[30:31], v[32:33]
	ds_bpermute_b32 v33, v146, v31
	ds_bpermute_b32 v32, v146, v30
	v_pk_mul_f32 v[4:5], v[10:11], v[144:145] op_sel_hi:[1,0]
	v_pk_fma_f32 v[12:13], v[12:13], v[120:121], v[102:103]
	v_pk_fma_f32 v[4:5], v[4:5], v[92:93], v[100:101]
	v_cvt_pk_bf16_f32 v6, v6, v7
	s_waitcnt lgkmcnt(0)
	v_pk_add_f32 v[30:31], v[30:31], v[32:33]
	ds_bpermute_b32 v33, v79, v31
	ds_bpermute_b32 v32, v79, v30
	v_cvt_pk_bf16_f32 v4, v4, v5
	v_cvt_pk_bf16_f32 v7, v8, v9
	v_pk_mul_f32 v[8:9], v[34:35], v[144:145] op_sel_hi:[1,0]
	v_pk_mul_f32 v[34:35], v[36:37], v[144:145] op_sel_hi:[1,0]
	s_waitcnt lgkmcnt(0)
; template <int R>
; DI void norm_rows(const Params& p, int layer, int which, int t0, int tstep, int lane) {
;     ...
;   for (int r = 0; r < R; ++r) ss[r] = rsqrtf(ss[r] * (1.f / 1024.f) + EPSV);
;   float4 mm[4], sh[4];
; #pragma unroll
;   for (int j = 0; j < 4; ++j) {
;     int col = lane * 4 + 256 * j;
;     float4 gg = *(const float4*)(g + col);
;     float4 sc = *(const float4*)(md + 1024 + col);
;     sh[j] = *(const float4*)(md + col);
;     mm[j] = make_float4(gg.x * (1.f + sc.x), gg.y * (1.f + sc.y), gg.z * (1.f + sc.z), gg.w * (1.f + sc.w));
;   }
; #pragma unroll
;   for (int j = 0; j < 4; ++j) {
;     int col = lane * 4 + 256 * j;
; #pragma unroll
;     for (int r = 0; r < R; ++r)
;       *(uint2*)(p.H + (size_t)(t0 + r * tstep) * LDK + col) =
;           make_uint2(pack_bf16(v[r][j].x * ss[r] * mm[j].x + sh[j].x, v[r][j].y * ss[r] * mm[j].y + sh[j].y),
;                      pack_bf16(v[r][j].z * ss[r] * mm[j].z + sh[j].z, v[r][j].w * ss[r] * mm[j].w + sh[j].w));
;   }
	v_pk_add_f32 v[10:11], v[30:31], v[32:33]
	v_pk_fma_f32 v[8:9], v[8:9], v[116:117], v[96:97]
	v_pk_fma_f32 v[10:11], v[10:11], s[16:17], v[104:105] op_sel_hi:[1,0,0]
	v_pk_fma_f32 v[34:35], v[34:35], v[118:119], v[98:99]
	v_mul_f32_e32 v5, 0x4b800000, v11
	v_cmp_gt_f32_e32 vcc, s14, v11
	v_cvt_pk_bf16_f32 v8, v8, v9
	v_cvt_pk_bf16_f32 v9, v34, v35
	v_cndmask_b32_e32 v5, v11, v5, vcc
	v_rsq_f32_e32 v11, v5
	v_cvt_pk_bf16_f32 v5, v12, v13
	v_mul_f32_e32 v12, 0x45800000, v11
	v_cndmask_b32_e32 v12, v11, v12, vcc
	v_pk_mul_f32 v[26:27], v[26:27], v[12:13] op_sel_hi:[1,0]
	v_pk_mul_f32 v[28:29], v[28:29], v[12:13] op_sel_hi:[1,0]
	v_pk_mul_f32 v[22:23], v[22:23], v[12:13] op_sel_hi:[1,0]
	v_pk_mul_f32 v[24:25], v[24:25], v[12:13] op_sel_hi:[1,0]
	v_pk_fma_f32 v[26:27], v[108:109], v[26:27], v[54:55]
	v_pk_fma_f32 v[28:29], v[28:29], v[110:111], v[56:57]
	v_pk_fma_f32 v[22:23], v[22:23], v[112:113], v[50:51]
	v_pk_fma_f32 v[24:25], v[24:25], v[114:115], v[52:53]
	v_cvt_pk_bf16_f32 v26, v26, v27
	v_cvt_pk_bf16_f32 v27, v28, v29
	v_cvt_pk_bf16_f32 v22, v22, v23
	v_cvt_pk_bf16_f32 v23, v24, v25
	v_pk_mul_f32 v[24:25], v[42:43], v[12:13] op_sel_hi:[1,0]
	v_pk_mul_f32 v[28:29], v[44:45], v[12:13] op_sel_hi:[1,0]
	v_mul_f32_e32 v11, 0x4b800000, v10
	v_cmp_gt_f32_e32 vcc, s14, v10
	v_pk_fma_f32 v[24:25], v[24:25], v[116:117], v[96:97]
	v_pk_fma_f32 v[28:29], v[28:29], v[118:119], v[98:99]
	v_cndmask_b32_e32 v10, v10, v11, vcc
	v_cvt_pk_bf16_f32 v24, v24, v25
	v_cvt_pk_bf16_f32 v25, v28, v29
	v_pk_mul_f32 v[28:29], v[38:39], v[12:13] op_sel_hi:[1,0]
	v_rsq_f32_e32 v13, v10
	v_pk_fma_f32 v[28:29], v[28:29], v[92:93], v[100:101]
	global_store_dwordx2 v[90:91], v[18:19], off
	global_store_dwordx2 v[88:89], v[20:21], off
	global_store_dwordx2 v[86:87], v[26:27], off
	v_cvt_pk_bf16_f32 v28, v28, v29
	v_pk_mul_f32 v[10:11], v[40:41], v[12:13] op_sel_hi:[1,0]
	s_nop 0
	v_pk_fma_f32 v[10:11], v[10:11], v[120:121], v[102:103]
	s_nop 0
	v_cvt_pk_bf16_f32 v29, v10, v11
	v_mul_f32_e32 v10, 0x45800000, v13
	v_cndmask_b32_e32 v10, v13, v10, vcc
	v_pk_mul_f32 v[12:13], v[62:63], v[10:11] op_sel_hi:[1,0]
	v_pk_mul_f32 v[18:19], v[64:65], v[10:11] op_sel_hi:[1,0]
	v_pk_fma_f32 v[12:13], v[108:109], v[12:13], v[54:55]
	v_pk_fma_f32 v[18:19], v[110:111], v[18:19], v[56:57]
	v_cvt_pk_bf16_f32 v12, v12, v13
	v_cvt_pk_bf16_f32 v13, v18, v19
	global_store_dwordx2 v[84:85], v[12:13], off
	global_store_dwordx2 v[90:91], v[14:15], off offset:512
	global_store_dwordx2 v[88:89], v[16:17], off offset:512
	global_store_dwordx2 v[86:87], v[22:23], off offset:512
	v_pk_mul_f32 v[12:13], v[58:59], v[10:11] op_sel_hi:[1,0]
	v_pk_mul_f32 v[14:15], v[60:61], v[10:11] op_sel_hi:[1,0]
	v_pk_fma_f32 v[12:13], v[12:13], v[112:113], v[50:51]
	v_pk_fma_f32 v[14:15], v[14:15], v[114:115], v[52:53]
	v_cvt_pk_bf16_f32 v12, v12, v13
	v_cvt_pk_bf16_f32 v13, v14, v15
	global_store_dwordx2 v[84:85], v[12:13], off offset:512
	global_store_dwordx2 v[90:91], v[6:7], off offset:1024
	global_store_dwordx2 v[88:89], v[8:9], off offset:1024
	global_store_dwordx2 v[86:87], v[24:25], off offset:1024
	v_pk_mul_f32 v[6:7], v[70:71], v[10:11] op_sel_hi:[1,0]
	v_pk_mul_f32 v[8:9], v[72:73], v[10:11] op_sel_hi:[1,0]
	v_pk_fma_f32 v[6:7], v[6:7], v[116:117], v[96:97]
	v_pk_fma_f32 v[8:9], v[8:9], v[118:119], v[98:99]
	v_cvt_pk_bf16_f32 v6, v6, v7
	v_cvt_pk_bf16_f32 v7, v8, v9
	global_store_dwordx2 v[84:85], v[6:7], off offset:1024
	global_store_dwordx2 v[90:91], v[2:3], off offset:1536
	global_store_dwordx2 v[88:89], v[4:5], off offset:1536
	global_store_dwordx2 v[86:87], v[28:29], off offset:1536
	v_pk_mul_f32 v[2:3], v[66:67], v[10:11] op_sel_hi:[1,0]
	v_pk_mul_f32 v[4:5], v[68:69], v[10:11] op_sel_hi:[1,0]
	v_pk_fma_f32 v[2:3], v[2:3], v[92:93], v[100:101]
	v_pk_fma_f32 v[4:5], v[4:5], v[120:121], v[102:103]
	v_cvt_pk_bf16_f32 v2, v2, v3
	v_cvt_pk_bf16_f32 v3, v4, v5
	global_store_dwordx2 v[84:85], v[2:3], off offset:1536
	s_branch .LBB0_196

; DI int tidx() { int t = threadIdx.x; asm volatile("" : "+v"(t)); return t; }
; DI void norm_dyn(const Params& p, int layer, int which, int row0, int row1, unsigned* ctr) {
;   const int tid = tidx(), lane = tid & 63, wid = tid >> 6;
;   const int nchunk = (row1 - row0) >> 5;
;   while (true) {
;     int ch = grab(ctr);
;     if (ch >= nchunk) break;
;     norm_rows<4>(p, layer, which, row0 + ch * 32 + wid, 8, lane);
.LBB0_876:
	v_readlane_b32 s0, v252, 35
	v_readlane_b32 s1, v252, 36
	s_mov_b32 s7, s1
	v_readlane_b32 s0, v254, 40
	v_readlane_b32 s1, v254, 41
	s_mov_b32 s1, s7
	s_mov_b32 s2, s0
	v_writelane_b32 v254, s2, 40
	s_lshl_b64 s[0:1], s[0:1], 2
	v_mov_b32_e32 v0, v213
	v_writelane_b32 v254, s3, 41
	s_add_u32 s2, s58, s0
	s_addc_u32 s3, s59, s1
	v_readlane_b32 s0, v254, 33
	v_readlane_b32 s1, v254, 34
	s_mov_b32 s1, s7
	s_mul_hi_u32 s5, s0, 5
	s_mul_i32 s4, s0, 5
	s_lshl_b32 s6, s0, 10
	v_writelane_b32 v252, s0, 35
	s_nop 0
	v_ashrrev_i32_e32 v104, 6, v0
	v_writelane_b32 v252, s1, 36
	v_lshlrev_b32_e32 v0, 2, v0
	v_readlane_b32 s12, v252, 19
	s_lshl_b64 s[0:1], s[6:7], 2
	v_readlane_b32 s24, v252, 31
	v_and_b32_e32 v2, 0xfc, v0
	v_readlane_b32 s25, v252, 32
	s_add_u32 s0, s24, s0
	s_addc_u32 s1, s25, s1
	v_lshlrev_b32_e32 v0, 2, v2
	v_or_b32_e32 v4, 0x100, v2
	v_or_b32_e32 v6, 0x200, v2
	v_or_b32_e32 v8, 0x300, v2
	s_waitcnt vmcnt(0)
	v_lshl_add_u64 v[74:75], s[0:1], 0, v[0:1]
	v_lshlrev_b32_e32 v0, 1, v2
	v_readlane_b32 s13, v252, 20
	v_readlane_b32 s16, v252, 23
	v_readlane_b32 s17, v252, 24
	v_lshl_add_u64 v[76:77], s[86:87], 0, v[0:1]
	v_lshlrev_b32_e32 v0, 2, v2
	v_lshlrev_b32_e32 v78, 2, v4
	v_lshlrev_b32_e32 v80, 2, v6
	v_lshlrev_b32_e32 v82, 2, v8
	v_readlane_b32 s14, v252, 21
	v_readlane_b32 s15, v252, 22
	v_readlane_b32 s18, v252, 25
	v_readlane_b32 s19, v252, 26
	v_readlane_b32 s20, v252, 27
	v_readlane_b32 s21, v252, 28
	v_readlane_b32 s22, v252, 29
	v_readlane_b32 s23, v252, 30
	v_readlane_b32 s26, v252, 33
	v_readlane_b32 s27, v252, 34
	v_readlane_b32 s6, v253, 43
	s_nop 3
	s_and_b32 s6, s6, 7
	s_lshl_b32 s7, s6, 8
	s_add_u32 s2, s2, s7
	s_addc_u32 s3, s3, 0
	s_add_u32 s2, s2, 0x100
	s_addc_u32 s3, s3, 0
	s_lshl_b32 s6, s6, 11
	v_add_u32_e32 v104, s6, v104
	s_branch .LBB0_878

; template <int R>
; DI void norm_rows(const Params& p, int layer, int which, int t0, int tstep, int lane) {
;   const float* g = (which ? p.norm_ffn : p.norm_attn) + layer * DM;
;   const float* md = p.mod + ((size_t)layer * 5 + mb_of(t0)) * 6144 + (which ? 3 * 1024 : 0);
;   float4 v[R][4];
;   float ss[R];
; #pragma unroll
;   for (int r = 0; r < R; ++r) {
;     const float* xr = which ? (const float*)xrow_dst(p, t0 + r * tstep) : xrow_src(p, layer, t0 + r * tstep);
; #pragma unroll
;     for (int j = 0; j < 4; ++j) v[r][j] = *(const float4*)(xr + lane * 4 + 256 * j);
; DI void norm_dyn(const Params& p, int layer, int which, int row0, int row1, unsigned* ctr) {
;     ...
;   while (true) {
;     int ch = grab(ctr);
;     if (ch >= nchunk) break;
;     norm_rows<4>(p, layer, which, row0 + ch * 32 + wid, 8, lane);
.LBB0_882:
	s_or_b64 exec, exec, s[0:1]
	s_waitcnt lgkmcnt(0)
	s_barrier
	ds_read_b32 v2, v1
	s_movk_i32 s0, 0x3f
	s_waitcnt lgkmcnt(0)
	s_barrier
	v_cmp_lt_i32_e32 vcc, s0, v2
	s_mov_b64 s[0:1], -1
	s_cbranch_vccnz .LBB0_877
	v_lshl_add_u32 v58, v2, 5, v104
	v_mov_b64_e32 v[2:3], s[12:13]
	v_mov_b64_e32 v[4:5], s[16:17]
	v_mov_b64_e32 v[6:7], s[76:77]
	v_mov_b64_e32 v[8:9], s[64:65]
	v_ashrrev_i32_e32 v59, 31, v58
	v_cndmask_b32_e64 v4, v8, v4, s[72:73]
	v_add_u32_e32 v8, 0xffffc000, v58
	v_cmp_gt_i32_e32 vcc, s28, v58
	v_cndmask_b32_e64 v5, v9, v5, s[72:73]
	v_cndmask_b32_e64 v6, v6, v2, s[72:73]
	v_cndmask_b32_e64 v7, v7, v3, s[72:73]
	v_cndmask_b32_e32 v3, 0, v59, vcc
	v_cndmask_b32_e32 v2, v8, v58, vcc
	v_cndmask_b32_e32 v5, v5, v7, vcc
	v_cndmask_b32_e32 v4, v4, v6, vcc
	v_lshlrev_b64 v[2:3], 12, v[2:3]
	v_add_u32_e32 v60, 8, v58
	s_movk_i32 s0, 0x3ff8
	v_lshl_add_u64 v[2:3], v[4:5], 0, v[2:3]
	v_add_u32_e32 v4, 0xffffc008, v58
	v_ashrrev_i32_e32 v61, 31, v60
	v_cmp_gt_i32_e32 vcc, s0, v58
	v_lshl_add_u64 v[2:3], v[2:3], 0, v[0:1]
	v_mov_b64_e32 v[12:13], s[12:13]
	v_cndmask_b32_e32 v5, 0, v61, vcc
	v_cndmask_b32_e32 v4, v4, v60, vcc
	v_mov_b64_e32 v[22:23], s[16:17]
	v_mov_b64_e32 v[24:25], s[76:77]
	v_mov_b64_e32 v[26:27], s[64:65]
	global_load_dwordx4 v[18:21], v[2:3], off
	global_load_dwordx4 v[14:17], v[2:3], off offset:1024
	v_lshlrev_b64 v[10:11], 12, v[4:5]
	global_load_dwordx4 v[6:9], v[2:3], off offset:2048
	s_nop 0
	global_load_dwordx4 v[2:5], v[2:3], off offset:3072
	v_add_u32_e32 v62, 16, v58
	v_cndmask_b32_e64 v22, v26, v22, s[72:73]
	v_cndmask_b32_e64 v23, v27, v23, s[72:73]
	v_cndmask_b32_e64 v12, v24, v12, s[72:73]
	v_cndmask_b32_e64 v13, v25, v13, s[72:73]
	v_cndmask_b32_e32 v13, v23, v13, vcc
	v_cndmask_b32_e32 v12, v22, v12, vcc
	v_lshl_add_u64 v[10:11], v[12:13], 0, v[10:11]
	v_lshl_add_u64 v[10:11], v[10:11], 0, v[0:1]
	s_movk_i32 s0, 0x3ff0
	v_add_u32_e32 v28, 0xffffc010, v58
	v_ashrrev_i32_e32 v63, 31, v62
	global_load_dwordx4 v[46:49], v[10:11], off
	global_load_dwordx4 v[30:33], v[10:11], off offset:1024
	v_cmp_gt_i32_e32 vcc, s0, v58
	v_mov_b64_e32 v[24:25], s[12:13]
	v_mov_b64_e32 v[26:27], s[16:17]
	v_cndmask_b32_e32 v13, 0, v63, vcc
	v_cndmask_b32_e32 v12, v28, v62, vcc
	v_lshlrev_b64 v[22:23], 12, v[12:13]
	global_load_dwordx4 v[34:37], v[10:11], off offset:2048
	s_nop 0
	global_load_dwordx4 v[10:13], v[10:11], off offset:3072
	v_mov_b64_e32 v[28:29], s[76:77]
	v_mov_b64_e32 v[38:39], s[64:65]
	v_add_u32_e32 v64, 24, v58
	v_cndmask_b32_e64 v26, v38, v26, s[72:73]
	v_cndmask_b32_e64 v27, v39, v27, s[72:73]
	v_cndmask_b32_e64 v24, v28, v24, s[72:73]
	v_cndmask_b32_e64 v25, v29, v25, s[72:73]
	s_movk_i32 s0, 0x3fe8
	v_add_u32_e32 v40, 0xffffc018, v58
	v_ashrrev_i32_e32 v65, 31, v64
	v_cndmask_b32_e32 v25, v27, v25, vcc
	v_cndmask_b32_e32 v24, v26, v24, vcc
	v_cmp_gt_i32_e32 vcc, s0, v58
	v_lshl_add_u64 v[22:23], v[24:25], 0, v[22:23]
	v_lshl_add_u64 v[38:39], v[22:23], 0, v[0:1]
	v_cndmask_b32_e32 v41, 0, v65, vcc
	v_cndmask_b32_e32 v40, v40, v64, vcc
	v_lshlrev_b64 v[66:67], 12, v[40:41]
	v_min_i32_e32 v40, 0x4000, v58
	v_ashrrev_i32_e32 v40, 12, v40
	v_ashrrev_i32_e32 v41, 31, v40
	global_load_dwordx4 v[26:29], v[38:39], off
	global_load_dwordx4 v[22:25], v[38:39], off offset:1024
	v_lshl_add_u64 v[68:69], s[4:5], 0, v[40:41]
	v_mov_b64_e32 v[40:41], s[62:63]
	s_movk_i32 s6, 0x6000
	v_mad_u64_u32 v[70:71], s[0:1], v68, s6, v[40:41]
	global_load_dwordx4 v[42:45], v[38:39], off offset:2048
	s_nop 0
	global_load_dwordx4 v[38:41], v[38:39], off offset:3072
	v_mad_i32_i24 v71, v69, s6, v71
	s_mov_b64 s[0:1], 0x1000
	v_lshl_add_u64 v[68:69], v[70:71], 0, s[0:1]
	v_mov_b64_e32 v[50:51], s[12:13]
	v_mov_b64_e32 v[52:53], s[76:77]
	v_mov_b64_e32 v[54:55], s[16:17]
	v_mov_b64_e32 v[56:57], s[64:65]
	v_lshl_add_u64 v[72:73], v[68:69], 0, v[0:1]
	v_lshlrev_b64 v[58:59], 11, v[58:59]
	global_load_dwordx4 v[106:109], v[72:73], off
	v_lshl_add_u64 v[90:91], v[76:77], 0, v[58:59]
	v_lshlrev_b64 v[58:59], 11, v[60:61]
	global_load_dwordx4 v[110:113], v[74:75], off
	v_lshl_add_u64 v[88:89], v[76:77], 0, v[58:59]
	v_lshlrev_b64 v[58:59], 11, v[62:63]
	v_lshl_add_u64 v[86:87], v[76:77], 0, v[58:59]
	v_lshlrev_b64 v[58:59], 11, v[64:65]
	v_lshl_add_u64 v[84:85], v[76:77], 0, v[58:59]
	v_cndmask_b32_e64 v54, v56, v54, s[72:73]
	v_cndmask_b32_e64 v55, v57, v55, s[72:73]
	v_cndmask_b32_e64 v50, v52, v50, s[72:73]
	v_cndmask_b32_e64 v51, v53, v51, s[72:73]
	v_cndmask_b32_e32 v51, v55, v51, vcc
	v_cndmask_b32_e32 v50, v54, v50, vcc
	v_lshl_add_u64 v[50:51], v[50:51], 0, v[66:67]
	s_waitcnt vmcnt(0) lgkmcnt(0)
; template <int R>
; DI void norm_rows(const Params& p, int layer, int which, int t0, int tstep, int lane) {
;     ...
; #pragma unroll
;   for (int r = 0; r < R; ++r) {
;     ss[r] = 0.f;
; #pragma unroll
;     for (int j = 0; j < 4; ++j) ss[r] += v[r][j].x * v[r][j].x + v[r][j].y * v[r][j].y + v[r][j].z * v[r][j].z + v[r][j].w * v[r][j].w;
;   }
; #pragma unroll
;   for (int o = 32; o >= 1; o >>= 1)
; #pragma unroll
;     for (int r = 0; r < R; ++r) ss[r] += __shfl_xor(ss[r], o);
; #pragma unroll
;   for (int r = 0; r < R; ++r) ss[r] = rsqrtf(ss[r] * (1.f / 1024.f) + EPSV);
;   float4 mm[4], sh[4];
; #pragma unroll
;   for (int j = 0; j < 4; ++j) {
;     int col = lane * 4 + 256 * j;
;     float4 gg = *(const float4*)(g + col);
;     float4 sc = *(const float4*)(md + 1024 + col);
;     sh[j] = *(const float4*)(md + col);
;     mm[j] = make_float4(gg.x * (1.f + sc.x), gg.y * (1.f + sc.y), gg.z * (1.f + sc.z), gg.w * (1.f + sc.w));
;   }
	v_mov_b32_e32 v64, v19
	v_mov_b32_e32 v65, v15
	v_mov_b32_e32 v62, v18
	v_mov_b32_e32 v63, v14
	v_pk_mul_f32 v[64:65], v[64:65], v[64:65]
	v_mov_b32_e32 v58, v20
	v_mov_b32_e32 v59, v16
	v_pk_fma_f32 v[62:63], v[62:63], v[62:63], v[64:65]
	v_mov_b32_e32 v94, v7
	v_mov_b32_e32 v95, v3
	v_mov_b32_e32 v60, v21
	v_mov_b32_e32 v61, v17
	v_pk_fma_f32 v[58:59], v[58:59], v[58:59], v[62:63]
	v_mov_b32_e32 v64, v6
	v_mov_b32_e32 v65, v2
	v_pk_mul_f32 v[94:95], v[94:95], v[94:95]
	v_pk_fma_f32 v[58:59], v[60:61], v[60:61], v[58:59]
	v_mov_b32_e32 v60, v8
	v_mov_b32_e32 v61, v4
	v_pk_fma_f32 v[64:65], v[64:65], v[64:65], v[94:95]
	v_mov_b32_e32 v96, v47
	v_mov_b32_e32 v97, v31
	v_mov_b32_e32 v62, v9
	v_mov_b32_e32 v63, v5
	v_pk_fma_f32 v[60:61], v[60:61], v[60:61], v[64:65]
	v_mov_b32_e32 v94, v46
	v_mov_b32_e32 v95, v30
	v_pk_mul_f32 v[96:97], v[96:97], v[96:97]
	v_mov_b32_e32 v79, v1
	v_pk_fma_f32 v[60:61], v[62:63], v[62:63], v[60:61]
	v_mov_b32_e32 v62, v48
	v_mov_b32_e32 v63, v32
	v_pk_fma_f32 v[94:95], v[94:95], v[94:95], v[96:97]
	v_mov_b32_e32 v98, v35
	v_mov_b32_e32 v99, v11
	v_lshl_add_u64 v[66:67], v[50:51], 0, v[0:1]
	v_and_b32_e32 v50, 64, v211
	v_lshl_add_u64 v[92:93], v[70:71], 0, v[0:1]
	v_lshl_add_u64 v[70:71], v[68:69], 0, v[78:79]
	v_mov_b32_e32 v64, v49
	v_mov_b32_e32 v65, v33
	v_pk_fma_f32 v[62:63], v[62:63], v[62:63], v[94:95]
	v_mov_b32_e32 v96, v34
	v_mov_b32_e32 v97, v10
	v_pk_mul_f32 v[98:99], v[98:99], v[98:99]
	v_add_u32_e32 v79, 64, v50
	v_xor_b32_e32 v50, 32, v211
	v_pk_fma_f32 v[62:63], v[64:65], v[64:65], v[62:63]
	v_mov_b32_e32 v64, v36
	v_mov_b32_e32 v65, v12
	v_pk_fma_f32 v[96:97], v[96:97], v[96:97], v[98:99]
	v_cmp_lt_i32_e32 vcc, v50, v79
	v_mov_b32_e32 v81, v1
	v_mov_b32_e32 v94, v37
	v_mov_b32_e32 v95, v13
	v_pk_fma_f32 v[64:65], v[64:65], v[64:65], v[96:97]
	v_cndmask_b32_e32 v50, v211, v50, vcc
	v_lshl_add_u64 v[122:123], v[68:69], 0, v[80:81]
	v_pk_fma_f32 v[64:65], v[94:95], v[94:95], v[64:65]
	v_lshlrev_b32_e32 v81, 2, v50
	v_mov_b32_e32 v50, v62
	v_mov_b32_e32 v51, v58
	v_mov_b32_e32 v58, v63
	v_pk_add_f32 v[50:51], v[50:51], v[58:59]
	v_mov_b32_e32 v52, v64
	v_mov_b32_e32 v53, v60
	v_pk_add_f32 v[50:51], v[50:51], v[52:53]
	v_mov_b32_e32 v60, v65
	v_pk_add_f32 v[50:51], v[50:51], v[60:61]
	ds_bpermute_b32 v53, v81, v51
	ds_bpermute_b32 v52, v81, v50
	v_xor_b32_e32 v72, 16, v211
	v_cmp_lt_i32_e32 vcc, v72, v79
	v_mov_b32_e32 v83, v1
	v_lshl_add_u64 v[68:69], v[68:69], 0, v[82:83]
	v_cndmask_b32_e32 v58, v211, v72, vcc
	v_lshlrev_b32_e32 v83, 2, v58
	s_waitcnt lgkmcnt(0)
	v_pk_add_f32 v[58:59], v[50:51], v[52:53]
	ds_bpermute_b32 v61, v83, v59
	ds_bpermute_b32 v60, v83, v58
	v_xor_b32_e32 v62, 8, v211
	v_cmp_lt_i32_e32 vcc, v62, v79
	global_load_dwordx4 v[114:117], v[70:71], off
	global_load_dwordx4 v[118:121], v[74:75], off offset:1024
	v_cndmask_b32_e32 v50, v211, v62, vcc
	global_load_dwordx4 v[122:125], v[122:123], off
	s_nop 0
	global_load_dwordx4 v[126:129], v[74:75], off offset:2048
	global_load_dwordx4 v[130:133], v[68:69], off
	global_load_dwordx4 v[134:137], v[74:75], off offset:3072
	v_lshlrev_b32_e32 v105, 2, v50
	s_waitcnt lgkmcnt(0)
	v_pk_add_f32 v[68:69], v[58:59], v[60:61]
	ds_bpermute_b32 v71, v105, v69
	ds_bpermute_b32 v70, v105, v68
	v_xor_b32_e32 v62, 4, v211
	v_cmp_lt_i32_e32 vcc, v62, v79
	v_xor_b32_e32 v72, 2, v211
	global_load_dwordx4 v[54:57], v[92:93], off
	global_load_dwordx4 v[50:53], v[92:93], off offset:1024
	v_cndmask_b32_e32 v58, v211, v62, vcc
	v_lshlrev_b32_e32 v143, 2, v58
	s_waitcnt lgkmcnt(0)
	v_pk_add_f32 v[68:69], v[68:69], v[70:71]
	ds_bpermute_b32 v71, v143, v69
	ds_bpermute_b32 v70, v143, v68
	global_load_dwordx4 v[62:65], v[66:67], off
	global_load_dwordx4 v[58:61], v[66:67], off offset:1024
	v_cmp_lt_i32_e32 vcc, v72, v79
	v_xor_b32_e32 v103, 1, v211
	v_mov_b32_e32 v100, v27
	v_cndmask_b32_e32 v72, v211, v72, vcc
	v_lshlrev_b32_e32 v145, 2, v72
	s_waitcnt lgkmcnt(0)
	v_pk_add_f32 v[138:139], v[68:69], v[70:71]
	global_load_dwordx4 v[70:73], v[66:67], off offset:2048
	s_nop 0
	global_load_dwordx4 v[66:69], v[66:67], off offset:3072
	ds_bpermute_b32 v141, v145, v139
	ds_bpermute_b32 v140, v145, v138
	v_cmp_lt_i32_e32 vcc, v103, v79
	v_mov_b32_e32 v101, v23
	v_mov_b32_e32 v98, v26
	v_cndmask_b32_e32 v79, v211, v103, vcc
	v_lshlrev_b32_e32 v79, 2, v79
	s_waitcnt lgkmcnt(0)
	v_pk_add_f32 v[138:139], v[138:139], v[140:141]
	ds_bpermute_b32 v141, v79, v139
	ds_bpermute_b32 v140, v79, v138
	v_mov_b32_e32 v99, v22
	v_pk_mul_f32 v[100:101], v[100:101], v[100:101]
	v_mov_b32_e32 v102, v43
	v_mov_b32_e32 v103, v39
	v_mov_b32_e32 v94, v28
	v_mov_b32_e32 v95, v24
	v_pk_fma_f32 v[98:99], v[98:99], v[98:99], v[100:101]
	v_mov_b32_e32 v100, v42
	v_mov_b32_e32 v101, v38
	v_pk_mul_f32 v[102:103], v[102:103], v[102:103]
	v_pk_fma_f32 v[94:95], v[94:95], v[94:95], v[98:99]
	v_mov_b32_e32 v98, v44
	v_mov_b32_e32 v99, v40
	v_pk_fma_f32 v[100:101], v[100:101], v[100:101], v[102:103]
	s_mov_b32 s0, 0x358637bd
	v_pk_fma_f32 v[98:99], v[98:99], v[98:99], v[100:101]
	s_waitcnt lgkmcnt(0)
	v_pk_add_f32 v[100:101], v[138:139], v[140:141]
	v_mov_b64_e32 v[138:139], s[0:1]
	s_mov_b32 s8, 0x3a800000
	v_pk_fma_f32 v[100:101], v[100:101], s[8:9], v[138:139] op_sel_hi:[1,0,0]
	s_mov_b32 s6, 0x800000
	v_mul_f32_e32 v102, 0x4b800000, v101
	v_cmp_gt_f32_e32 vcc, s6, v101
	v_cmp_gt_f32_e64 s[0:1], s6, v100
	v_mov_b32_e32 v96, v29
	v_cndmask_b32_e32 v101, v101, v102, vcc
	v_mul_f32_e32 v102, 0x4b800000, v100
	v_rsq_f32_e32 v101, v101
	v_cndmask_b32_e64 v100, v100, v102, s[0:1]
	v_rsq_f32_e32 v100, v100
	v_mov_b32_e32 v97, v25
	v_pk_fma_f32 v[94:95], v[96:97], v[96:97], v[94:95]
	v_mov_b32_e32 v96, v45
	v_mov_b32_e32 v97, v41
	v_pk_fma_f32 v[140:141], v[96:97], v[96:97], v[98:99]
	v_mul_f32_e32 v96, 0x45800000, v101
	v_cndmask_b32_e32 v142, v101, v96, vcc
	v_mul_f32_e32 v96, 0x45800000, v100
	v_cndmask_b32_e64 v144, v100, v96, s[0:1]
	v_pk_add_f32 v[100:101], v[106:107], 1.0 op_sel_hi:[1,0]
	global_load_dwordx4 v[96:99], v[92:93], off offset:2048
	v_pk_mul_f32 v[106:107], v[110:111], v[100:101]
	v_pk_add_f32 v[100:101], v[108:109], 1.0 op_sel_hi:[1,0]
	s_waitcnt vmcnt(0)
; template <int R>
; DI void norm_rows(const Params& p, int layer, int which, int t0, int tstep, int lane) {
;     ...
; #pragma unroll
;   for (int r = 0; r < R; ++r) {
;     ss[r] = 0.f;
; #pragma unroll
;     for (int j = 0; j < 4; ++j) ss[r] += v[r][j].x * v[r][j].x + v[r][j].y * v[r][j].y + v[r][j].z * v[r][j].z + v[r][j].w * v[r][j].w;
;   }
; #pragma unroll
;   for (int o = 32; o >= 1; o >>= 1)
; #pragma unroll
;     for (int r = 0; r < R; ++r) ss[r] += __shfl_xor(ss[r], o);
; #pragma unroll
;   for (int r = 0; r < R; ++r) ss[r] = rsqrtf(ss[r] * (1.f / 1024.f) + EPSV);
;   float4 mm[4], sh[4];
; #pragma unroll
;   for (int j = 0; j < 4; ++j) {
;     int col = lane * 4 + 256 * j;
;     float4 gg = *(const float4*)(g + col);
;     float4 sc = *(const float4*)(md + 1024 + col);
;     sh[j] = *(const float4*)(md + col);
;     mm[j] = make_float4(gg.x * (1.f + sc.x), gg.y * (1.f + sc.y), gg.z * (1.f + sc.z), gg.w * (1.f + sc.w));
;   }
; #pragma unroll
;   for (int j = 0; j < 4; ++j) {
;     int col = lane * 4 + 256 * j;
; #pragma unroll
;     for (int r = 0; r < R; ++r)
;       *(uint2*)(p.H + (size_t)(t0 + r * tstep) * LDK + col) =
;           make_uint2(pack_bf16(v[r][j].x * ss[r] * mm[j].x + sh[j].x, v[r][j].y * ss[r] * mm[j].y + sh[j].y),
;                      pack_bf16(v[r][j].z * ss[r] * mm[j].z + sh[j].z, v[r][j].w * ss[r] * mm[j].w + sh[j].w));
	v_pk_add_f32 v[110:111], v[116:117], 1.0 op_sel_hi:[1,0]
	v_pk_mul_f32 v[108:109], v[112:113], v[100:101]
	global_load_dwordx4 v[100:103], v[92:93], off offset:3072
	v_pk_add_f32 v[92:93], v[114:115], 1.0 op_sel_hi:[1,0]
	v_pk_mul_f32 v[18:19], v[18:19], v[142:143] op_sel_hi:[1,0]
	v_pk_mul_f32 v[20:21], v[20:21], v[142:143] op_sel_hi:[1,0]
	v_pk_mul_f32 v[92:93], v[118:119], v[92:93]
	v_pk_mul_f32 v[110:111], v[120:121], v[110:111]
	v_pk_mul_f32 v[14:15], v[14:15], v[142:143] op_sel_hi:[1,0]
	v_pk_mul_f32 v[16:17], v[16:17], v[142:143] op_sel_hi:[1,0]
	v_pk_add_f32 v[112:113], v[122:123], 1.0 op_sel_hi:[1,0]
	v_pk_mul_f32 v[32:33], v[32:33], v[144:145] op_sel_hi:[1,0]
	v_pk_fma_f32 v[18:19], v[18:19], v[106:107], v[54:55]
	v_pk_fma_f32 v[20:21], v[20:21], v[108:109], v[56:57]
	v_cvt_pk_bf16_f32 v18, v18, v19
	v_cvt_pk_bf16_f32 v19, v20, v21
	v_pk_mul_f32 v[20:21], v[46:47], v[144:145] op_sel_hi:[1,0]
	v_pk_mul_f32 v[46:47], v[48:49], v[144:145] op_sel_hi:[1,0]
	v_mov_b32_e32 v120, v63
	v_mov_b32_e32 v121, v59
	v_pk_fma_f32 v[14:15], v[14:15], v[92:93], v[50:51]
	v_pk_fma_f32 v[16:17], v[16:17], v[110:111], v[52:53]
	v_mov_b32_e32 v48, v62
	v_mov_b32_e32 v49, v58
	v_pk_mul_f32 v[120:121], v[120:121], v[120:121]
	v_pk_fma_f32 v[20:21], v[106:107], v[20:21], v[54:55]
	v_pk_fma_f32 v[46:47], v[46:47], v[108:109], v[56:57]
	v_cvt_pk_bf16_f32 v14, v14, v15
	v_cvt_pk_bf16_f32 v15, v16, v17
	v_pk_mul_f32 v[16:17], v[30:31], v[144:145] op_sel_hi:[1,0]
	v_mov_b32_e32 v30, v64
	v_mov_b32_e32 v31, v60
	v_pk_fma_f32 v[48:49], v[48:49], v[48:49], v[120:121]
	v_mov_b32_e32 v122, v71
	v_mov_b32_e32 v123, v67
	v_cvt_pk_bf16_f32 v20, v20, v21
	v_cvt_pk_bf16_f32 v21, v46, v47
	v_mov_b32_e32 v46, v65
	v_mov_b32_e32 v47, v61
	v_pk_fma_f32 v[30:31], v[30:31], v[30:31], v[48:49]
	v_mov_b32_e32 v120, v70
	v_mov_b32_e32 v121, v66
	v_pk_mul_f32 v[122:123], v[122:123], v[122:123]
	v_pk_fma_f32 v[30:31], v[46:47], v[46:47], v[30:31]
	v_mov_b32_e32 v46, v72
	v_mov_b32_e32 v47, v68
	v_pk_fma_f32 v[120:121], v[120:121], v[120:121], v[122:123]
	v_mov_b32_e32 v48, v73
	v_mov_b32_e32 v49, v69
	v_pk_fma_f32 v[46:47], v[46:47], v[46:47], v[120:121]
	v_pk_fma_f32 v[16:17], v[16:17], v[92:93], v[50:51]
	v_pk_fma_f32 v[46:47], v[48:49], v[48:49], v[46:47]
	v_mov_b32_e32 v48, v30
	v_mov_b32_e32 v49, v94
	v_mov_b32_e32 v94, v31
	v_pk_add_f32 v[30:31], v[48:49], v[94:95]
	v_mov_b32_e32 v48, v46
	v_mov_b32_e32 v49, v140
	v_pk_add_f32 v[30:31], v[30:31], v[48:49]
	v_mov_b32_e32 v140, v47
	v_pk_add_f32 v[30:31], v[30:31], v[140:141]
	ds_bpermute_b32 v47, v81, v31
	ds_bpermute_b32 v46, v81, v30
	v_pk_fma_f32 v[32:33], v[32:33], v[110:111], v[52:53]
	v_cvt_pk_bf16_f32 v16, v16, v17
	v_cvt_pk_bf16_f32 v17, v32, v33
	v_pk_add_f32 v[116:117], v[130:131], 1.0 op_sel_hi:[1,0]
	s_waitcnt lgkmcnt(0)
	v_pk_add_f32 v[30:31], v[30:31], v[46:47]
	ds_bpermute_b32 v33, v83, v31
	ds_bpermute_b32 v32, v83, v30
	v_pk_add_f32 v[118:119], v[132:133], 1.0 op_sel_hi:[1,0]
	v_pk_mul_f32 v[116:117], v[134:135], v[116:117]
	v_pk_mul_f32 v[118:119], v[136:137], v[118:119]
	v_pk_mul_f32 v[2:3], v[2:3], v[142:143] op_sel_hi:[1,0]
	s_waitcnt lgkmcnt(0)
	v_pk_add_f32 v[30:31], v[30:31], v[32:33]
	ds_bpermute_b32 v33, v105, v31
	ds_bpermute_b32 v32, v105, v30
	v_pk_mul_f32 v[4:5], v[4:5], v[142:143] op_sel_hi:[1,0]
	v_pk_mul_f32 v[12:13], v[12:13], v[144:145] op_sel_hi:[1,0]
	v_pk_add_f32 v[114:115], v[124:125], 1.0 op_sel_hi:[1,0]
	v_pk_mul_f32 v[112:113], v[126:127], v[112:113]
	s_waitcnt lgkmcnt(0)
	v_pk_add_f32 v[30:31], v[30:31], v[32:33]
	ds_bpermute_b32 v33, v143, v31
	ds_bpermute_b32 v32, v143, v30
	s_waitcnt vmcnt(0)
	v_pk_fma_f32 v[2:3], v[2:3], v[116:117], v[100:101]
	v_pk_fma_f32 v[4:5], v[4:5], v[118:119], v[102:103]
	v_cvt_pk_bf16_f32 v2, v2, v3
	v_cvt_pk_bf16_f32 v3, v4, v5
	s_waitcnt lgkmcnt(0)
	v_pk_add_f32 v[30:31], v[30:31], v[32:33]
	ds_bpermute_b32 v33, v145, v31
	ds_bpermute_b32 v32, v145, v30
	v_pk_mul_f32 v[4:5], v[10:11], v[144:145] op_sel_hi:[1,0]
	v_pk_fma_f32 v[12:13], v[12:13], v[118:119], v[102:103]
	v_pk_fma_f32 v[4:5], v[4:5], v[116:117], v[100:101]
	v_pk_mul_f32 v[114:115], v[128:129], v[114:115]
	s_waitcnt lgkmcnt(0)
	v_pk_add_f32 v[30:31], v[30:31], v[32:33]
	ds_bpermute_b32 v33, v79, v31
	ds_bpermute_b32 v32, v79, v30
	v_cvt_pk_bf16_f32 v4, v4, v5
	v_pk_mul_f32 v[6:7], v[6:7], v[142:143] op_sel_hi:[1,0]
	v_pk_mul_f32 v[8:9], v[8:9], v[142:143] op_sel_hi:[1,0]
	v_pk_fma_f32 v[6:7], v[6:7], v[112:113], v[96:97]
	s_waitcnt lgkmcnt(0)
; template <int R>
; DI void norm_rows(const Params& p, int layer, int which, int t0, int tstep, int lane) {
;     ...
;   for (int r = 0; r < R; ++r) ss[r] = rsqrtf(ss[r] * (1.f / 1024.f) + EPSV);
;   float4 mm[4], sh[4];
; #pragma unroll
;   for (int j = 0; j < 4; ++j) {
;     int col = lane * 4 + 256 * j;
;     float4 gg = *(const float4*)(g + col);
;     float4 sc = *(const float4*)(md + 1024 + col);
;     sh[j] = *(const float4*)(md + col);
;     mm[j] = make_float4(gg.x * (1.f + sc.x), gg.y * (1.f + sc.y), gg.z * (1.f + sc.z), gg.w * (1.f + sc.w));
;   }
; #pragma unroll
;   for (int j = 0; j < 4; ++j) {
;     int col = lane * 4 + 256 * j;
; #pragma unroll
;     for (int r = 0; r < R; ++r)
;       *(uint2*)(p.H + (size_t)(t0 + r * tstep) * LDK + col) =
;           make_uint2(pack_bf16(v[r][j].x * ss[r] * mm[j].x + sh[j].x, v[r][j].y * ss[r] * mm[j].y + sh[j].y),
;                      pack_bf16(v[r][j].z * ss[r] * mm[j].z + sh[j].z, v[r][j].w * ss[r] * mm[j].w + sh[j].w));
;   }
	v_pk_add_f32 v[10:11], v[30:31], v[32:33]
	v_pk_fma_f32 v[8:9], v[8:9], v[114:115], v[98:99]
	v_pk_fma_f32 v[10:11], v[10:11], s[8:9], v[138:139] op_sel_hi:[1,0,0]
	v_cvt_pk_bf16_f32 v6, v6, v7
	v_mul_f32_e32 v5, 0x4b800000, v11
	v_cmp_gt_f32_e32 vcc, s6, v11
	v_cvt_pk_bf16_f32 v7, v8, v9
	v_pk_mul_f32 v[8:9], v[34:35], v[144:145] op_sel_hi:[1,0]
	v_cndmask_b32_e32 v5, v11, v5, vcc
	v_rsq_f32_e32 v11, v5
	v_cvt_pk_bf16_f32 v5, v12, v13
	v_pk_mul_f32 v[34:35], v[36:37], v[144:145] op_sel_hi:[1,0]
	v_pk_fma_f32 v[8:9], v[8:9], v[112:113], v[96:97]
	v_mul_f32_e32 v12, 0x45800000, v11
	v_cndmask_b32_e32 v12, v11, v12, vcc
	v_pk_mul_f32 v[26:27], v[26:27], v[12:13] op_sel_hi:[1,0]
	v_pk_mul_f32 v[28:29], v[28:29], v[12:13] op_sel_hi:[1,0]
	v_pk_mul_f32 v[22:23], v[22:23], v[12:13] op_sel_hi:[1,0]
	v_pk_mul_f32 v[24:25], v[24:25], v[12:13] op_sel_hi:[1,0]
	v_pk_fma_f32 v[26:27], v[106:107], v[26:27], v[54:55]
	v_pk_fma_f32 v[28:29], v[28:29], v[108:109], v[56:57]
	v_pk_fma_f32 v[22:23], v[22:23], v[92:93], v[50:51]
	v_pk_fma_f32 v[24:25], v[24:25], v[110:111], v[52:53]
	v_cvt_pk_bf16_f32 v26, v26, v27
	v_cvt_pk_bf16_f32 v27, v28, v29
	v_cvt_pk_bf16_f32 v22, v22, v23
	v_cvt_pk_bf16_f32 v23, v24, v25
	v_pk_mul_f32 v[24:25], v[42:43], v[12:13] op_sel_hi:[1,0]
	v_pk_mul_f32 v[28:29], v[44:45], v[12:13] op_sel_hi:[1,0]
	v_mul_f32_e32 v11, 0x4b800000, v10
	v_cmp_gt_f32_e32 vcc, s6, v10
	v_pk_fma_f32 v[24:25], v[24:25], v[112:113], v[96:97]
	v_pk_fma_f32 v[28:29], v[28:29], v[114:115], v[98:99]
	v_cndmask_b32_e32 v10, v10, v11, vcc
	v_cvt_pk_bf16_f32 v24, v24, v25
	v_cvt_pk_bf16_f32 v25, v28, v29
	v_pk_mul_f32 v[28:29], v[38:39], v[12:13] op_sel_hi:[1,0]
	v_rsq_f32_e32 v13, v10
	v_pk_fma_f32 v[28:29], v[28:29], v[116:117], v[100:101]
	global_store_dwordx2 v[90:91], v[18:19], off
	global_store_dwordx2 v[88:89], v[20:21], off
	global_store_dwordx2 v[86:87], v[26:27], off
	v_cvt_pk_bf16_f32 v28, v28, v29
	v_pk_mul_f32 v[10:11], v[40:41], v[12:13] op_sel_hi:[1,0]
	v_pk_fma_f32 v[34:35], v[34:35], v[114:115], v[98:99]
	v_pk_fma_f32 v[10:11], v[10:11], v[118:119], v[102:103]
	v_cvt_pk_bf16_f32 v8, v8, v9
	v_cvt_pk_bf16_f32 v29, v10, v11
	v_mul_f32_e32 v10, 0x45800000, v13
	v_cndmask_b32_e32 v10, v13, v10, vcc
	v_pk_mul_f32 v[12:13], v[62:63], v[10:11] op_sel_hi:[1,0]
	v_pk_mul_f32 v[18:19], v[64:65], v[10:11] op_sel_hi:[1,0]
	v_pk_fma_f32 v[12:13], v[106:107], v[12:13], v[54:55]
	v_pk_fma_f32 v[18:19], v[108:109], v[18:19], v[56:57]
	v_cvt_pk_bf16_f32 v12, v12, v13
	v_cvt_pk_bf16_f32 v13, v18, v19
	global_store_dwordx2 v[84:85], v[12:13], off
	global_store_dwordx2 v[90:91], v[14:15], off offset:512
	global_store_dwordx2 v[88:89], v[16:17], off offset:512
	global_store_dwordx2 v[86:87], v[22:23], off offset:512
	v_pk_mul_f32 v[12:13], v[58:59], v[10:11] op_sel_hi:[1,0]
	v_pk_mul_f32 v[14:15], v[60:61], v[10:11] op_sel_hi:[1,0]
	v_pk_fma_f32 v[12:13], v[12:13], v[92:93], v[50:51]
	v_pk_fma_f32 v[14:15], v[14:15], v[110:111], v[52:53]
	v_cvt_pk_bf16_f32 v9, v34, v35
	v_cvt_pk_bf16_f32 v12, v12, v13
	v_cvt_pk_bf16_f32 v13, v14, v15
	global_store_dwordx2 v[84:85], v[12:13], off offset:512
	global_store_dwordx2 v[90:91], v[6:7], off offset:1024
	global_store_dwordx2 v[88:89], v[8:9], off offset:1024
	global_store_dwordx2 v[86:87], v[24:25], off offset:1024
	v_pk_mul_f32 v[6:7], v[70:71], v[10:11] op_sel_hi:[1,0]
	v_pk_mul_f32 v[8:9], v[72:73], v[10:11] op_sel_hi:[1,0]
	v_pk_fma_f32 v[6:7], v[6:7], v[112:113], v[96:97]
	v_pk_fma_f32 v[8:9], v[8:9], v[114:115], v[98:99]
	v_cvt_pk_bf16_f32 v6, v6, v7
	v_cvt_pk_bf16_f32 v7, v8, v9
	global_store_dwordx2 v[84:85], v[6:7], off offset:1024
	global_store_dwordx2 v[90:91], v[2:3], off offset:1536
	global_store_dwordx2 v[88:89], v[4:5], off offset:1536
	global_store_dwordx2 v[86:87], v[28:29], off offset:1536
	v_pk_mul_f32 v[2:3], v[66:67], v[10:11] op_sel_hi:[1,0]
	v_pk_mul_f32 v[4:5], v[68:69], v[10:11] op_sel_hi:[1,0]
	v_pk_fma_f32 v[2:3], v[2:3], v[116:117], v[100:101]
	v_pk_fma_f32 v[4:5], v[4:5], v[118:119], v[102:103]
	v_cvt_pk_bf16_f32 v2, v2, v3
	v_cvt_pk_bf16_f32 v3, v4, v5
	s_mov_b64 s[0:1], 0
	global_store_dwordx2 v[84:85], v[2:3], off offset:1536
	s_branch .LBB0_877
